# leadernowait: xcd barrier leader path with early L1 invalidate and no wait on the per-XCD release atomic; experimental
# speedup vs baseline: 1.0009x; 1.0009x over previous
;   __host__ __device__ __forceinline__ unsigned* bar() const { return (unsigned*)(wsl() + OFF_BAR); }
; __device__ __forceinline__ unsigned xb_ld(unsigned* p)              { return __hip_atomic_load(p, __ATOMIC_RELAXED, __HIP_MEMORY_SCOPE_AGENT); }
; __device__ __forceinline__ unsigned xb_add(unsigned* p, unsigned v) { return __hip_atomic_fetch_add(p, v, __ATOMIC_RELAXED, __HIP_MEMORY_SCOPE_AGENT); }
; #define XB_SPIN(cond, bar) do { unsigned _sp = 0; while (cond) { __builtin_amdgcn_s_sleep(1); \
;     if ((++_sp & 255u) == 0u) { if (xb_ld(&(bar)[XB_TMO])) break; if (_sp > XB_SPIN_CAP) { atomicAdd(&(bar)[XB_TMO], 1u); break; } } } } while (0)
; __device__ __forceinline__ void xcd_barrier(const XcdBarrier& b) {
;     ...
;             xb_add(&bar[XB_XGEN(b.x)], 1u);
;             asm volatile("s_waitcnt vmcnt(0)" ::: "memory");
;         } else {
;             XB_SPIN(xb_ld(&bar[XB_XGEN(b.x)]) == gen, bar);
;             __builtin_amdgcn_fence(__ATOMIC_ACQUIRE, "agent");
;             asm volatile("s_waitcnt vmcnt(0)" ::: "memory");
;         }
;     }
;     __syncthreads();
.LBB0_1124:
	s_or_b64 exec, exec, s[4:5]
.LBB0_1125:
	s_or_b64 exec, exec, s[0:1]
	s_waitcnt lgkmcnt(0)
	s_barrier
	s_getpc_b64 s[98:99]
